# first grid barrier through the XCD-hierarchical barrier instead of cooperative-groups grid.sync (on top of v22 cache-policy edits)
# speedup vs baseline: 1.0229x; 1.0038x over previous
; __device__ __forceinline__ void xcd_barrier(const XcdBarrier& b) {
;     asm volatile("s_waitcnt vmcnt(0)" ::: "memory");
;     __syncthreads();
;     if (threadIdx.x == 0) {
;         unsigned* bar = b.bar;
;         __builtin_amdgcn_s_waitcnt(0);
;         unsigned nloc = b.st[0], nx = b.st[1];
;         if (nloc == 0u) { xcd_barrier_complete(bar, b.x, nloc, nx); b.st[0] = nloc; b.st[1] = nx; }
; __global__ void __launch_bounds__(NWAVES * 64, 2) fwd_mega(Args args) {
;     ...
;         if (ph > args.ph_lo) { for (int rs_ = 0; rs_ < REP_SYNC; ++rs_) { if (ph == args.ph_lo + 1) grid.sync(); else xcd_barrier(bar); } }
.LBB0_141:
	s_cmp_le_i32 s61, s50
	s_cbranch_scc1 .LBB0_205
	v_readlane_b32 s0, v253, 5
	s_cmp_lg_u32 s61, s0
	s_mov_b64 s[0:1], -1
	s_waitcnt vmcnt(0)
	s_barrier
	s_mov_b64 s[6:7], exec
	v_readlane_b32 s0, v254, 29
	v_readlane_b32 s1, v254, 30
	s_and_b64 s[0:1], s[6:7], s[0:1]
	s_mov_b64 exec, s[0:1]
	s_cbranch_execz .LBB0_191
	v_readlane_b32 s0, v253, 2
	s_waitcnt vmcnt(0) expcnt(0) lgkmcnt(0)
	s_nop 0
	v_mov_b32_e32 v1, s0
	ds_read_b32 v3, v1
	ds_read_b32 v1, v1 offset:4
	s_waitcnt lgkmcnt(1)
	v_cmp_ne_u32_e32 vcc, 0, v3
	s_cbranch_vccnz .LBB0_159
	s_mov_b32 s3, 1
	s_branch .LBB0_147
